# ctx outproj gemm_tile K-loop: fragments read up front, early buffer-release barrier, LDS-DMA two steps ahead (same structure as the inproj remainder tiles)
# speedup vs baseline: 1.0187x; 1.0040x over previous
; DI int otid() { int t = threadIdx.x; asm volatile("" : "+v"(t)); return t; }
;   const int tid_full = otid(); const int tid = tid_full & 255; lds += (tid_full >> 8) * HALF_LDS;
;   const int lane = tid & 63, w = tid >> 6, l31 = lane & 31, h = lane >> 5;
;   const int wr = w >> 1, wc = w & 1;
;   const int lrow = tid >> 3, lch = (tid & 7) ^ ((tid >> 4) & 7);
;   const bf16_t* ag = A + (size_t)lrow * lda + lch * 8;
;   const bf16_t* bg = Bt + (size_t)lrow * ldb + lch * 8;
;   const size_t a32 = (size_t)32 * lda, b32 = (size_t)32 * ldb;
;   f32x16 acc[2][2];
; #pragma unroll
;   for (int i = 0; i < 2; ++i)
; #pragma unroll
;     for (int j = 0; j < 2; ++j)
; #pragma unroll
;       for (int e = 0; e < 16; ++e) acc[i][j][e] = 0.f;
;   const int nk = K >> 6;
;   const int rsw = (l31 >> 1) & 7;
;   const int aoff = (wr * 64 + l31) * 128, boff = 16384 + (wc * 64 + l31) * 128;
;   char* ldst = lds + tid * 16;
;     ...
;   G_DMA(0, 0);
; DI void phase_outproj(KP p, int l, char* lds) {
;     ...
;       const int item = 2 * j + hb; const int bb = 2 * xcd + (item >> 4), m128 = (item >> 3) & 1, nt = item & 7;
;       const int m0 = (bb * 18 + 16 + m128) * 128, n0 = nt * 128;
;       const float* src = p->ctx + ((size_t)bb * CL + m128 * 128) * 1024;
;       float* dst = ctx1 + ((size_t)bb * CL + m128 * 128) * 1024;
;       const float* gt = mod + (size_t)16 * 3072 + 2048;
;       gemm_tile(Y + (size_t)m0 * 1024, 1024, wo + (size_t)n0 * 1024, 1024, 1024, lds, [&](int m, int n, f32x4 v) {
.LBB0_356:
	s_bitcmp1_b32 s49, 3
	s_cselect_b64 s[44:45], -1, 0
	s_lshl_b32 s42, s48, 11
	s_and_b32 s56, s42, 0x1c0000
	s_lshl_b32 s42, s50, 1
	s_add_i32 s47, s42, s2
	s_ashr_i32 s64, s47, 4
	v_readlane_b32 s42, v253, 5
	s_add_i32 s42, s64, s42
	s_bfe_u32 s46, s47, 0x10003
	s_mul_i32 s51, s42, 18
	s_or_b32 s46, s51, s46
	s_lshl_b32 s46, s46, 7
	s_addk_i32 s46, 0x800
	s_lshl_b32 s47, s47, 7
	s_and_b32 s51, s47, 0x380
	s_ashr_i32 s47, s46, 31
	s_lshr_b32 s43, s48, 7
	s_bfe_u32 s57, s49, 0x10003
	s_lshl_b64 s[46:47], s[46:47], 11
	v_mov_b32_e32 v76, v196
	s_add_u32 s46, s34, s46
	s_mov_b32 s65, 0x11000
	v_lshrrev_b32_e32 v0, 8, v76
	v_lshrrev_b32_e32 v11, 4, v76
	v_mov_b32_e32 v8, 4
	s_addc_u32 s47, s35, s47
	s_lshl_b32 s54, s51, 11
	v_mul_i32_i24_e32 v74, 0x11000, v0
	v_mad_i32_i24 v77, v0, s65, 0
	v_xor_b32_e32 v0, v11, v76
	v_lshlrev_b32_e32 v2, 8, v76
	v_lshlrev_b32_sdwa v8, v8, v76 dst_sel:DWORD dst_unused:UNUSED_PAD src0_sel:DWORD src1_sel:BYTE_0
	s_add_u32 s54, s52, s54
	v_and_b32_e32 v2, 0xf800, v2
	v_mov_b32_e32 v3, v1
	v_lshlrev_b32_e32 v0, 4, v0
	v_add_u32_e32 v80, v77, v8
	s_addc_u32 s55, s53, 0
	v_lshl_add_u64 v[6:7], s[46:47], 0, v[2:3]
	v_and_b32_e32 v0, 0x70, v0
	v_add_u32_e32 v81, 0x4000, v80
	v_readfirstlane_b32 s46, v80
	v_lshl_add_u64 v[4:5], s[54:55], 0, v[2:3]
	v_lshl_add_u64 v[6:7], v[6:7], 0, v[0:1]
	s_mov_b32 m0, s46
	v_readfirstlane_b32 s46, v81
	v_add_u32_e32 v82, 0x1000, v80
	v_lshl_add_u64 v[4:5], v[4:5], 0, v[0:1]
	global_load_lds_dwordx4 v[6:7], off
	s_mov_b32 m0, s46
	s_mov_b64 s[54:55], 0x10000
	v_readfirstlane_b32 s46, v82
	v_add_u32_e32 v83, 0x5000, v80
	global_load_lds_dwordx4 v[4:5], off
	v_lshl_add_u64 v[8:9], v[6:7], 0, s[54:55]
	s_mov_b32 m0, s46
	v_readfirstlane_b32 s46, v83
	v_add_u32_e32 v84, 0x2000, v80
	global_load_lds_dwordx4 v[8:9], off
	v_lshl_add_u64 v[8:9], v[4:5], 0, s[54:55]
	s_mov_b32 m0, s46
	s_mov_b64 s[54:55], 0x20000
	v_readfirstlane_b32 s46, v84
	v_add_u32_e32 v85, 0x6000, v80
	global_load_lds_dwordx4 v[8:9], off
	v_lshl_add_u64 v[8:9], v[6:7], 0, s[54:55]
	s_mov_b32 m0, s46
	v_readfirstlane_b32 s46, v85
	v_add_u32_e32 v86, 0x3000, v80
	global_load_lds_dwordx4 v[8:9], off
	v_lshl_add_u64 v[8:9], v[4:5], 0, s[54:55]
	s_mov_b32 m0, s46
	s_mov_b64 s[54:55], 0x30000
	v_readfirstlane_b32 s46, v86
	v_add_u32_e32 v87, 0x7000, v80
	global_load_lds_dwordx4 v[8:9], off
	v_lshl_add_u64 v[6:7], v[6:7], 0, s[54:55]
	s_mov_b32 m0, s46
	v_readfirstlane_b32 s46, v87
	global_load_lds_dwordx4 v[6:7], off
	v_lshl_add_u64 v[4:5], v[4:5], 0, s[54:55]
	s_mov_b32 m0, s46
	s_add_u32 s46, s20, s56
	global_load_lds_dwordx4 v[4:5], off
	s_addc_u32 s47, s21, 0
	v_lshl_add_u64 v[66:67], s[46:47], 0, v[2:3]
	s_mul_i32 s64, s64, 18
	v_readlane_b32 s46, v254, 56
	s_add_i32 s46, s46, s64
	v_and_b32_e32 v75, 31, v76
	v_lshrrev_b32_e32 v0, 1, v76
	s_add_i32 s46, s46, s57
	v_and_or_b32 v79, v0, 64, v75
	v_lshlrev_b32_e32 v0, 7, v76
	s_lshl_b32 s46, s46, 7
	v_bfe_u32 v78, v76, 5, 1
	v_and_b32_e32 v0, 0x2f80, v0
	v_bfe_u32 v4, v76, 1, 3
	s_ashr_i32 s47, s46, 31
	v_add_u32_e32 v90, v77, v0
	v_bitop3_b32 v0, v78, v4, 2 bitop3:0x36
	s_lshl_b64 s[46:47], s[46:47], 11
	v_lshlrev_b32_e32 v91, 4, v0
	v_bitop3_b32 v0, v78, v4, 4 bitop3:0x36
	s_add_u32 s46, s36, s46
	v_lshrrev_b32_e32 v10, 5, v76
	v_lshlrev_b32_e32 v92, 4, v0
	v_bitop3_b32 v0, v78, v4, 6 bitop3:0x36
	s_addc_u32 s47, s37, s47
	v_bitop3_b32 v5, v10, v4, 1 bitop3:0x6c
	v_lshlrev_b32_e32 v93, 4, v0
	v_bitop3_b32 v0, v11, 7, v76 bitop3:0x48
	v_lshl_add_u64 v[68:69], s[46:47], 0, v[2:3]
	v_mov_b32_e32 v2, 0
	v_lshlrev_b32_e32 v88, 4, v5
	v_lshl_add_u32 v89, v79, 7, v77
	v_lshlrev_b32_e32 v0, 4, v0
; #define G_WAIT() { asm volatile("s_waitcnt vmcnt(0)" ::: "memory"); __syncthreads(); }
;     ...
;   f32x16 acc[2][2];
; #pragma unroll
;   for (int i = 0; i < 2; ++i)
; #pragma unroll
;     for (int j = 0; j < 2; ++j)
; #pragma unroll
;       for (int e = 0; e < 16; ++e) acc[i][j][e] = 0.f;
;   const int nk = K >> 6;
;   const int rsw = (l31 >> 1) & 7;
;   const int aoff = (wr * 64 + l31) * 128, boff = 16384 + (wc * 64 + l31) * 128;
;   char* ldst = lds + tid * 16;
;     ...
;   G_DMA(0, 0);
;   G_WAIT();
;   for (int kt = 0; kt < nk; kt += 2) {
;     if (kt + 1 < nk) G_DMA(1, kt + 1);
	v_add_u32_e32 v250, 0x8000, v80
	v_lshl_add_u64 v[248:249], v[68:69], 0, v[0:1]
	v_readfirstlane_b32 s55, v250
	s_mov_b64 s[56:57], 0x18b5180
	v_lshl_add_u64 v[248:249], v[248:249], 0, s[56:57]
	s_mov_b32 m0, s55
	s_nop 0
	global_load_lds_dwordx4 v[248:249], off
	v_add_u32_e32 v250, 0xc000, v80
	v_lshl_add_u64 v[248:249], v[66:67], 0, v[0:1]
	v_readfirstlane_b32 s55, v250
	s_mov_b64 s[56:57], 0xc31180
	v_lshl_add_u64 v[248:249], v[248:249], 0, s[56:57]
	s_mov_b32 m0, s55
	s_nop 0
	global_load_lds_dwordx4 v[248:249], off
	v_add_u32_e32 v250, 0x9000, v80
	v_lshl_add_u64 v[248:249], v[68:69], 0, v[0:1]
	v_readfirstlane_b32 s55, v250
	s_mov_b64 s[56:57], 0x18c5180
	v_lshl_add_u64 v[248:249], v[248:249], 0, s[56:57]
	s_mov_b32 m0, s55
	s_nop 0
	global_load_lds_dwordx4 v[248:249], off
	v_add_u32_e32 v250, 0xd000, v80
	v_lshl_add_u64 v[248:249], v[66:67], 0, v[0:1]
	v_readfirstlane_b32 s55, v250
	s_mov_b64 s[56:57], 0xc41180
	v_lshl_add_u64 v[248:249], v[248:249], 0, s[56:57]
	s_mov_b32 m0, s55
	s_nop 0
	global_load_lds_dwordx4 v[248:249], off
	v_add_u32_e32 v250, 0xa000, v80
	v_lshl_add_u64 v[248:249], v[68:69], 0, v[0:1]
	v_readfirstlane_b32 s55, v250
	s_mov_b64 s[56:57], 0x18d5180
	v_lshl_add_u64 v[248:249], v[248:249], 0, s[56:57]
	s_mov_b32 m0, s55
	s_nop 0
	global_load_lds_dwordx4 v[248:249], off
	v_add_u32_e32 v250, 0xe000, v80
	v_lshl_add_u64 v[248:249], v[66:67], 0, v[0:1]
	v_readfirstlane_b32 s55, v250
	s_mov_b64 s[56:57], 0xc51180
	v_lshl_add_u64 v[248:249], v[248:249], 0, s[56:57]
	s_mov_b32 m0, s55
	s_nop 0
	global_load_lds_dwordx4 v[248:249], off
	v_add_u32_e32 v250, 0xb000, v80
	v_lshl_add_u64 v[248:249], v[68:69], 0, v[0:1]
	v_readfirstlane_b32 s55, v250
	s_mov_b64 s[56:57], 0x18e5180
	v_lshl_add_u64 v[248:249], v[248:249], 0, s[56:57]
	s_mov_b32 m0, s55
	s_nop 0
	global_load_lds_dwordx4 v[248:249], off
	v_add_u32_e32 v250, 0xf000, v80
	v_lshl_add_u64 v[248:249], v[66:67], 0, v[0:1]
	v_readfirstlane_b32 s55, v250
	s_mov_b64 s[56:57], 0xc61180
	v_lshl_add_u64 v[248:249], v[248:249], 0, s[56:57]
	s_mov_b32 m0, s55
	s_nop 0
	global_load_lds_dwordx4 v[248:249], off
	s_mov_b32 s54, 0
	v_mov_b32_e32 v3, v2
	v_mov_b32_e32 v4, v2
	v_mov_b32_e32 v5, v2
	v_mov_b32_e32 v6, v2
	v_mov_b32_e32 v7, v2
	v_mov_b32_e32 v8, v2
	v_mov_b32_e32 v9, v2
	v_mov_b32_e32 v10, v2
	v_mov_b32_e32 v11, v2
	v_mov_b32_e32 v12, v2
	v_mov_b32_e32 v13, v2
	v_mov_b32_e32 v14, v2
	v_mov_b32_e32 v15, v2
	v_mov_b32_e32 v16, v2
	v_mov_b32_e32 v17, v2
	v_mov_b32_e32 v18, v2
	v_mov_b32_e32 v19, v2
	v_mov_b32_e32 v20, v2
	v_mov_b32_e32 v21, v2
	v_mov_b32_e32 v22, v2
	v_mov_b32_e32 v23, v2
	v_mov_b32_e32 v24, v2
	v_mov_b32_e32 v25, v2
	v_mov_b32_e32 v26, v2
	v_mov_b32_e32 v27, v2
	v_mov_b32_e32 v28, v2
	v_mov_b32_e32 v29, v2
	v_mov_b32_e32 v30, v2
	v_mov_b32_e32 v31, v2
	v_mov_b32_e32 v32, v2
	v_mov_b32_e32 v33, v2
	v_mov_b32_e32 v34, v2
	v_mov_b32_e32 v35, v2
	v_mov_b32_e32 v36, v2
	v_mov_b32_e32 v37, v2
	v_mov_b32_e32 v38, v2
	v_mov_b32_e32 v39, v2
	v_mov_b32_e32 v40, v2
	v_mov_b32_e32 v41, v2
	v_mov_b32_e32 v42, v2
	v_mov_b32_e32 v43, v2
	v_mov_b32_e32 v44, v2
	v_mov_b32_e32 v45, v2
	v_mov_b32_e32 v46, v2
	v_mov_b32_e32 v47, v2
	v_mov_b32_e32 v48, v2
	v_mov_b32_e32 v49, v2
	v_mov_b32_e32 v50, v2
	v_mov_b32_e32 v51, v2
	v_mov_b32_e32 v52, v2
	v_mov_b32_e32 v53, v2
	v_mov_b32_e32 v54, v2
	v_mov_b32_e32 v55, v2
	v_mov_b32_e32 v56, v2
	v_mov_b32_e32 v57, v2
	v_mov_b32_e32 v58, v2
	v_mov_b32_e32 v59, v2
	v_mov_b32_e32 v60, v2
	v_mov_b32_e32 v61, v2
	v_mov_b32_e32 v62, v2
	v_mov_b32_e32 v63, v2
	v_mov_b32_e32 v64, v2
	v_mov_b32_e32 v65, v2
	s_waitcnt vmcnt(8) lgkmcnt(0)
	s_barrier

; #define G_WAIT() { asm volatile("s_waitcnt vmcnt(0)" ::: "memory"); __syncthreads(); }
;     ...
;   for (int kt = 0; kt < nk; kt += 2) {
;     if (kt + 1 < nk) G_DMA(1, kt + 1);
;     G_COMPUTE(0);
;     G_WAIT();
;     if (kt + 1 < nk) {
;       if (kt + 2 < nk) G_DMA(0, kt + 2);
;       G_COMPUTE(1);
;       G_WAIT();
.Lco_loop:
	ds_read_b128 v[128:131], v160 offset:16384
	ds_read_b128 v[132:135], v160 offset:20480
	ds_read_b128 v[136:139], v192 offset:0
	ds_read_b128 v[140:143], v192 offset:4096
	ds_read_b128 v[144:147], v161 offset:16384
	ds_read_b128 v[148:151], v161 offset:20480
	ds_read_b128 v[152:155], v193 offset:0
	ds_read_b128 v[156:159], v193 offset:4096
	ds_read_b128 v[216:219], v190 offset:16384
	ds_read_b128 v[220:223], v190 offset:20480
	ds_read_b128 v[224:227], v194 offset:0
	ds_read_b128 v[228:231], v194 offset:4096
	ds_read_b128 v[232:235], v191 offset:16384
	ds_read_b128 v[236:239], v191 offset:20480
	ds_read_b128 v[240:243], v195 offset:0
	ds_read_b128 v[244:247], v195 offset:4096
	s_waitcnt lgkmcnt(0)
	s_barrier
	s_cmp_lt_u32 s54, 14
	s_cbranch_scc0 .Lco_a_nodma
	v_mov_b32_e32 v250, v80
	v_lshl_add_u64 v[248:249], v[68:69], 0, v[0:1]
	v_readfirstlane_b32 s55, v250
	s_mov_b64 s[56:57], 0x18b5200
	v_lshl_add_u64 v[248:249], v[248:249], 0, s[56:57]
	s_mov_b32 m0, s55
	s_nop 0
	global_load_lds_dwordx4 v[248:249], off
	v_mfma_f32_32x32x16_bf16 v[50:65], v[128:131], v[136:139], v[50:65]
	v_mfma_f32_32x32x16_bf16 v[34:49], v[132:135], v[136:139], v[34:49]
	v_add_u32_e32 v250, 0x4000, v80
	v_lshl_add_u64 v[248:249], v[66:67], 0, v[0:1]
	v_readfirstlane_b32 s55, v250
	s_mov_b64 s[56:57], 0xc31200
	v_lshl_add_u64 v[248:249], v[248:249], 0, s[56:57]
	s_mov_b32 m0, s55
	s_nop 0
	global_load_lds_dwordx4 v[248:249], off
	v_mfma_f32_32x32x16_bf16 v[18:33], v[128:131], v[140:143], v[18:33]
	v_mfma_f32_32x32x16_bf16 v[2:17], v[132:135], v[140:143], v[2:17]
	v_add_u32_e32 v250, 0x1000, v80
	v_lshl_add_u64 v[248:249], v[68:69], 0, v[0:1]
	v_readfirstlane_b32 s55, v250
	s_mov_b64 s[56:57], 0x18c5200
	v_lshl_add_u64 v[248:249], v[248:249], 0, s[56:57]
	s_mov_b32 m0, s55
	s_nop 0
	global_load_lds_dwordx4 v[248:249], off
	v_mfma_f32_32x32x16_bf16 v[50:65], v[144:147], v[152:155], v[50:65]
	v_mfma_f32_32x32x16_bf16 v[34:49], v[148:151], v[152:155], v[34:49]
	v_add_u32_e32 v250, 0x5000, v80
	v_lshl_add_u64 v[248:249], v[66:67], 0, v[0:1]
	v_readfirstlane_b32 s55, v250
	s_mov_b64 s[56:57], 0xc41200
	v_lshl_add_u64 v[248:249], v[248:249], 0, s[56:57]
	s_mov_b32 m0, s55
	s_nop 0
	global_load_lds_dwordx4 v[248:249], off
	v_mfma_f32_32x32x16_bf16 v[18:33], v[144:147], v[156:159], v[18:33]
	v_mfma_f32_32x32x16_bf16 v[2:17], v[148:151], v[156:159], v[2:17]
	v_add_u32_e32 v250, 0x2000, v80
	v_lshl_add_u64 v[248:249], v[68:69], 0, v[0:1]
	v_readfirstlane_b32 s55, v250
	s_mov_b64 s[56:57], 0x18d5200
	v_lshl_add_u64 v[248:249], v[248:249], 0, s[56:57]
	s_mov_b32 m0, s55
	s_nop 0
	global_load_lds_dwordx4 v[248:249], off
	v_mfma_f32_32x32x16_bf16 v[50:65], v[216:219], v[224:227], v[50:65]
	v_mfma_f32_32x32x16_bf16 v[34:49], v[220:223], v[224:227], v[34:49]
	v_add_u32_e32 v250, 0x6000, v80
	v_lshl_add_u64 v[248:249], v[66:67], 0, v[0:1]
	v_readfirstlane_b32 s55, v250
	s_mov_b64 s[56:57], 0xc51200
	v_lshl_add_u64 v[248:249], v[248:249], 0, s[56:57]
	s_mov_b32 m0, s55
	s_nop 0
	global_load_lds_dwordx4 v[248:249], off
	v_mfma_f32_32x32x16_bf16 v[18:33], v[216:219], v[228:231], v[18:33]
	v_mfma_f32_32x32x16_bf16 v[2:17], v[220:223], v[228:231], v[2:17]
	v_add_u32_e32 v250, 0x3000, v80
	v_lshl_add_u64 v[248:249], v[68:69], 0, v[0:1]
	v_readfirstlane_b32 s55, v250
	s_mov_b64 s[56:57], 0x18e5200
	v_lshl_add_u64 v[248:249], v[248:249], 0, s[56:57]
	s_mov_b32 m0, s55
	s_nop 0
	global_load_lds_dwordx4 v[248:249], off
	v_mfma_f32_32x32x16_bf16 v[50:65], v[232:235], v[240:243], v[50:65]
	v_mfma_f32_32x32x16_bf16 v[34:49], v[236:239], v[240:243], v[34:49]
	v_add_u32_e32 v250, 0x7000, v80
	v_lshl_add_u64 v[248:249], v[66:67], 0, v[0:1]
	v_readfirstlane_b32 s55, v250
	s_mov_b64 s[56:57], 0xc61200
	v_lshl_add_u64 v[248:249], v[248:249], 0, s[56:57]
	s_mov_b32 m0, s55
	s_nop 0
	global_load_lds_dwordx4 v[248:249], off
	v_mfma_f32_32x32x16_bf16 v[18:33], v[232:235], v[244:247], v[18:33]
	v_mfma_f32_32x32x16_bf16 v[2:17], v[236:239], v[244:247], v[2:17]
	s_waitcnt vmcnt(8)
	s_barrier
	s_branch .Lco_b

; #define G_WAIT() { asm volatile("s_waitcnt vmcnt(0)" ::: "memory"); __syncthreads(); }
;     ...
;     if (kt + 1 < nk) {
;       if (kt + 2 < nk) G_DMA(0, kt + 2);
;       G_COMPUTE(1);
;       G_WAIT();
;     }
;   }
.Lco_b:
	ds_read_b128 v[128:131], v160 offset:49152
	ds_read_b128 v[132:135], v160 offset:53248
	ds_read_b128 v[136:139], v192 offset:32768
	ds_read_b128 v[140:143], v192 offset:36864
	ds_read_b128 v[144:147], v161 offset:49152
	ds_read_b128 v[148:151], v161 offset:53248
	ds_read_b128 v[152:155], v193 offset:32768
	ds_read_b128 v[156:159], v193 offset:36864
	ds_read_b128 v[216:219], v190 offset:49152
	ds_read_b128 v[220:223], v190 offset:53248
	ds_read_b128 v[224:227], v194 offset:32768
	ds_read_b128 v[228:231], v194 offset:36864
	ds_read_b128 v[232:235], v191 offset:49152
	ds_read_b128 v[236:239], v191 offset:53248
	ds_read_b128 v[240:243], v195 offset:32768
	ds_read_b128 v[244:247], v195 offset:36864
	s_waitcnt lgkmcnt(0)
	s_barrier
	s_cmp_lt_u32 s54, 13
	s_cbranch_scc0 .Lco_b_nodma
	v_add_u32_e32 v250, 0x8000, v80
	v_lshl_add_u64 v[248:249], v[68:69], 0, v[0:1]
	v_readfirstlane_b32 s55, v250
	s_mov_b64 s[56:57], 0x18b5280
	v_lshl_add_u64 v[248:249], v[248:249], 0, s[56:57]
	s_mov_b32 m0, s55
	s_nop 0
	global_load_lds_dwordx4 v[248:249], off
	v_mfma_f32_32x32x16_bf16 v[50:65], v[128:131], v[136:139], v[50:65]
	v_mfma_f32_32x32x16_bf16 v[34:49], v[132:135], v[136:139], v[34:49]
	v_add_u32_e32 v250, 0xc000, v80
	v_lshl_add_u64 v[248:249], v[66:67], 0, v[0:1]
	v_readfirstlane_b32 s55, v250
	s_mov_b64 s[56:57], 0xc31280
	v_lshl_add_u64 v[248:249], v[248:249], 0, s[56:57]
	s_mov_b32 m0, s55
	s_nop 0
	global_load_lds_dwordx4 v[248:249], off
	v_mfma_f32_32x32x16_bf16 v[18:33], v[128:131], v[140:143], v[18:33]
	v_mfma_f32_32x32x16_bf16 v[2:17], v[132:135], v[140:143], v[2:17]
	v_add_u32_e32 v250, 0x9000, v80
	v_lshl_add_u64 v[248:249], v[68:69], 0, v[0:1]
	v_readfirstlane_b32 s55, v250
	s_mov_b64 s[56:57], 0x18c5280
	v_lshl_add_u64 v[248:249], v[248:249], 0, s[56:57]
	s_mov_b32 m0, s55
	s_nop 0
	global_load_lds_dwordx4 v[248:249], off
	v_mfma_f32_32x32x16_bf16 v[50:65], v[144:147], v[152:155], v[50:65]
	v_mfma_f32_32x32x16_bf16 v[34:49], v[148:151], v[152:155], v[34:49]
	v_add_u32_e32 v250, 0xd000, v80
	v_lshl_add_u64 v[248:249], v[66:67], 0, v[0:1]
	v_readfirstlane_b32 s55, v250
	s_mov_b64 s[56:57], 0xc41280
	v_lshl_add_u64 v[248:249], v[248:249], 0, s[56:57]
	s_mov_b32 m0, s55
	s_nop 0
	global_load_lds_dwordx4 v[248:249], off
	v_mfma_f32_32x32x16_bf16 v[18:33], v[144:147], v[156:159], v[18:33]
	v_mfma_f32_32x32x16_bf16 v[2:17], v[148:151], v[156:159], v[2:17]
	v_add_u32_e32 v250, 0xa000, v80
	v_lshl_add_u64 v[248:249], v[68:69], 0, v[0:1]
	v_readfirstlane_b32 s55, v250
	s_mov_b64 s[56:57], 0x18d5280
	v_lshl_add_u64 v[248:249], v[248:249], 0, s[56:57]
	s_mov_b32 m0, s55
	s_nop 0
	global_load_lds_dwordx4 v[248:249], off
	v_mfma_f32_32x32x16_bf16 v[50:65], v[216:219], v[224:227], v[50:65]
	v_mfma_f32_32x32x16_bf16 v[34:49], v[220:223], v[224:227], v[34:49]
	v_add_u32_e32 v250, 0xe000, v80
	v_lshl_add_u64 v[248:249], v[66:67], 0, v[0:1]
	v_readfirstlane_b32 s55, v250
	s_mov_b64 s[56:57], 0xc51280
	v_lshl_add_u64 v[248:249], v[248:249], 0, s[56:57]
	s_mov_b32 m0, s55
	s_nop 0
	global_load_lds_dwordx4 v[248:249], off
	v_mfma_f32_32x32x16_bf16 v[18:33], v[216:219], v[228:231], v[18:33]
	v_mfma_f32_32x32x16_bf16 v[2:17], v[220:223], v[228:231], v[2:17]
	v_add_u32_e32 v250, 0xb000, v80
	v_lshl_add_u64 v[248:249], v[68:69], 0, v[0:1]
	v_readfirstlane_b32 s55, v250
	s_mov_b64 s[56:57], 0x18e5280
	v_lshl_add_u64 v[248:249], v[248:249], 0, s[56:57]
	s_mov_b32 m0, s55
	s_nop 0
	global_load_lds_dwordx4 v[248:249], off
	v_mfma_f32_32x32x16_bf16 v[50:65], v[232:235], v[240:243], v[50:65]
	v_mfma_f32_32x32x16_bf16 v[34:49], v[236:239], v[240:243], v[34:49]
	v_add_u32_e32 v250, 0xf000, v80
	v_lshl_add_u64 v[248:249], v[66:67], 0, v[0:1]
	v_readfirstlane_b32 s55, v250
	s_mov_b64 s[56:57], 0xc61280
	v_lshl_add_u64 v[248:249], v[248:249], 0, s[56:57]
	s_mov_b32 m0, s55
	s_nop 0
	global_load_lds_dwordx4 v[248:249], off
	v_mfma_f32_32x32x16_bf16 v[18:33], v[232:235], v[244:247], v[18:33]
	v_mfma_f32_32x32x16_bf16 v[2:17], v[236:239], v[244:247], v[2:17]
	s_waitcnt vmcnt(8)
	s_barrier
	v_lshl_add_u64 v[68:69], v[68:69], 0, s[22:23]
	v_lshl_add_u64 v[66:67], v[66:67], 0, s[22:23]
	s_add_i32 s54, s54, 2
	s_branch .Lco_loop
.Lco_b_nodma:
	v_mfma_f32_32x32x16_bf16 v[50:65], v[128:131], v[136:139], v[50:65]
	v_mfma_f32_32x32x16_bf16 v[34:49], v[132:135], v[136:139], v[34:49]
	v_mfma_f32_32x32x16_bf16 v[18:33], v[128:131], v[140:143], v[18:33]
	v_mfma_f32_32x32x16_bf16 v[2:17], v[132:135], v[140:143], v[2:17]
	v_mfma_f32_32x32x16_bf16 v[50:65], v[144:147], v[152:155], v[50:65]
	v_mfma_f32_32x32x16_bf16 v[34:49], v[148:151], v[152:155], v[34:49]
	v_mfma_f32_32x32x16_bf16 v[18:33], v[144:147], v[156:159], v[18:33]
	v_mfma_f32_32x32x16_bf16 v[2:17], v[148:151], v[156:159], v[2:17]
	v_mfma_f32_32x32x16_bf16 v[50:65], v[216:219], v[224:227], v[50:65]
	v_mfma_f32_32x32x16_bf16 v[34:49], v[220:223], v[224:227], v[34:49]
	v_mfma_f32_32x32x16_bf16 v[18:33], v[216:219], v[228:231], v[18:33]
	v_mfma_f32_32x32x16_bf16 v[2:17], v[220:223], v[228:231], v[2:17]
	v_mfma_f32_32x32x16_bf16 v[50:65], v[232:235], v[240:243], v[50:65]
	v_mfma_f32_32x32x16_bf16 v[34:49], v[236:239], v[240:243], v[34:49]
	v_mfma_f32_32x32x16_bf16 v[18:33], v[232:235], v[244:247], v[18:33]
	v_mfma_f32_32x32x16_bf16 v[2:17], v[236:239], v[244:247], v[2:17]
	s_branch .LBB0_360
;     ...
;   float* ct = (float*)lds;
; #pragma unroll
;   for (int i = 0; i < 2; ++i)
; #pragma unroll
;     for (int j = 0; j < 2; ++j)
; #pragma unroll
;       for (int q = 0; q < 4; ++q) {
;         f32x4 v = {acc[i][j][4 * q], acc[i][j][4 * q + 1], acc[i][j][4 * q + 2], acc[i][j][4 * q + 3]};
;         *(f32x4*)(ct + (wr * 64 + i * 32 + l31) * 132 + wc * 64 + j * 32 + 8 * q + 4 * h) = v;
;       }
;   __syncthreads();
; #pragma unroll 4
;   for (int it = 0; it < 16; ++it) {
;     const int idx = it * 256 + tid; const int row = idx >> 5, c4 = (idx & 31) * 4;
;     f32x4 v = *(const f32x4*)(ct + row * 132 + c4);
;     epi(row, c4, v);
;   }
; DI void phase_outproj(KP p, int l, char* lds) {
;     ...
;       gemm_tile(Y + (size_t)m0 * 1024, 1024, wo + (size_t)n0 * 1024, 1024, 1024, lds, [&](int m, int n, f32x4 v) {
;         const size_t o = (size_t)m * 1024 + n0 + n;
;         f32x4 xv = *(const f32x4*)(src + o), g = *(const f32x4*)(gt + n0 + n);
;         f32x4 r = {xv[0] + g[0] * v[0], xv[1] + g[1] * v[1], xv[2] + g[2] * v[2], xv[3] + g[3] * v[3]};
;         *(f32x4*)(dst + o) = r; });
.LBB0_360:
	v_cndmask_b32_e64 v0, 0, 1, s[44:45]
	v_lshlrev_b32_e32 v66, 19, v0
	v_and_b32_e32 v0, 64, v76
	v_lshl_add_u32 v0, v0, 2, v77
	v_lshlrev_b32_e32 v67, 4, v78
	v_mul_u32_u24_e32 v68, 0x210, v79
	s_and_b32 s43, s43, 7
	v_add3_u32 v0, v0, v67, v68
	s_lshl_b32 s46, s43, 7
	s_ashr_i32 s43, s42, 31
	ds_write_b128 v0, v[50:53]
	ds_write_b128 v0, v[54:57] offset:32
	ds_write_b128 v0, v[58:61] offset:64
	ds_write_b128 v0, v[62:65] offset:96
	ds_write_b128 v0, v[34:37] offset:128
	ds_write_b128 v0, v[38:41] offset:160
	ds_write_b128 v0, v[42:45] offset:192
	ds_write_b128 v0, v[46:49] offset:224
	ds_write_b128 v0, v[18:21] offset:16896
	ds_write_b128 v0, v[22:25] offset:16928
	ds_write_b128 v0, v[26:29] offset:16960
	ds_write_b128 v0, v[30:33] offset:16992
	ds_write_b128 v0, v[2:5] offset:17024
	ds_write_b128 v0, v[6:9] offset:17056
	ds_write_b128 v0, v[10:13] offset:17088
	ds_write_b128 v0, v[14:17] offset:17120
	v_lshlrev_b32_e32 v0, 2, v76
	s_lshl_b32 s44, s51, 2
	v_and_b32_e32 v4, 0x7c, v0
	s_add_u32 s44, s18, s44
	s_addc_u32 s45, s19, 0
	v_lshlrev_b32_e32 v0, 2, v4
	v_lshl_add_u64 v[2:3], s[44:45], 0, v[0:1]
	v_mov_b32_e32 v0, 5
	v_lshrrev_b32_sdwa v20, v0, v76 dst_sel:DWORD dst_unused:UNUSED_PAD src0_sel:DWORD src1_sel:BYTE_0
	v_lshlrev_b32_e32 v0, 10, v20
	v_or3_b32 v0, v0, s46, v4
	s_lshl_b64 s[42:43], s[42:43], 20
	v_lshlrev_b32_e32 v18, 2, v0
	v_or_b32_e32 v16, s42, v66
	v_mov_b32_e32 v17, s43
	v_or_b32_e32 v0, 0x18000, v18
	v_lshl_add_u64 v[6:7], v[16:17], 0, v[0:1]
	v_or_b32_e32 v0, 0x10000, v18
	v_lshl_add_u64 v[10:11], v[16:17], 0, v[0:1]
	v_or_b32_e32 v0, 0x8000, v18
	v_mov_b32_e32 v19, v1
	s_movk_i32 s42, 0x210
	v_lshl_add_u64 v[14:15], v[16:17], 0, v[0:1]
	v_lshl_add_u64 v[18:19], v[16:17], 0, v[18:19]
	v_mad_u32_u24 v0, v20, s42, v74
	v_lshlrev_b32_e32 v20, 4, v75
	v_lshl_add_u64 v[4:5], s[40:41], 0, v[6:7]
	v_lshl_add_u64 v[6:7], s[4:5], 0, v[6:7]
	v_lshl_add_u64 v[8:9], s[40:41], 0, v[10:11]
	v_lshl_add_u64 v[10:11], s[4:5], 0, v[10:11]
	v_lshl_add_u64 v[12:13], s[40:41], 0, v[14:15]
	v_lshl_add_u64 v[14:15], s[4:5], 0, v[14:15]
	v_lshl_add_u64 v[16:17], s[40:41], 0, v[18:19]
	v_lshl_add_u64 v[18:19], s[4:5], 0, v[18:19]
	v_add3_u32 v0, v0, v20, 0
	s_mov_b64 s[42:43], 0
	s_waitcnt lgkmcnt(0)
	s_barrier
	global_load_dwordx4 v[232:235], v[2:3], off
	s_mov_b32 s47, 0
	s_mov_b32 s46, 0x0
	v_lshl_add_u64 v[34:35], v[18:19], 0, s[46:47]
	global_load_dwordx4 v[112:115], v[34:35], off
	s_mov_b32 s46, 0x0
	v_lshl_add_u64 v[34:35], v[14:15], 0, s[46:47]
	global_load_dwordx4 v[116:119], v[34:35], off
	s_mov_b32 s46, 0x0
	v_lshl_add_u64 v[34:35], v[10:11], 0, s[46:47]
	global_load_dwordx4 v[120:123], v[34:35], off
	s_mov_b32 s46, 0x0
	v_lshl_add_u64 v[34:35], v[6:7], 0, s[46:47]
	global_load_dwordx4 v[124:127], v[34:35], off
	s_mov_b32 s46, 0x20000
	v_lshl_add_u64 v[34:35], v[18:19], 0, s[46:47]
	global_load_dwordx4 v[128:131], v[34:35], off
	s_mov_b32 s46, 0x20000
	v_lshl_add_u64 v[34:35], v[14:15], 0, s[46:47]
	global_load_dwordx4 v[132:135], v[34:35], off
	s_mov_b32 s46, 0x20000
	v_lshl_add_u64 v[34:35], v[10:11], 0, s[46:47]
	global_load_dwordx4 v[136:139], v[34:35], off
	s_mov_b32 s46, 0x20000
	v_lshl_add_u64 v[34:35], v[6:7], 0, s[46:47]
	global_load_dwordx4 v[140:143], v[34:35], off
	s_mov_b32 s46, 0x40000
	v_lshl_add_u64 v[34:35], v[18:19], 0, s[46:47]
	global_load_dwordx4 v[144:147], v[34:35], off
	s_mov_b32 s46, 0x40000
	v_lshl_add_u64 v[34:35], v[14:15], 0, s[46:47]
	global_load_dwordx4 v[148:151], v[34:35], off
	s_mov_b32 s46, 0x40000
	v_lshl_add_u64 v[34:35], v[10:11], 0, s[46:47]
	global_load_dwordx4 v[152:155], v[34:35], off
	s_mov_b32 s46, 0x40000
	v_lshl_add_u64 v[34:35], v[6:7], 0, s[46:47]
	global_load_dwordx4 v[156:159], v[34:35], off
	s_mov_b32 s46, 0x60000
	v_lshl_add_u64 v[34:35], v[18:19], 0, s[46:47]
	global_load_dwordx4 v[216:219], v[34:35], off
	s_mov_b32 s46, 0x60000
	v_lshl_add_u64 v[34:35], v[14:15], 0, s[46:47]
	global_load_dwordx4 v[220:223], v[34:35], off
	s_mov_b32 s46, 0x60000
	v_lshl_add_u64 v[34:35], v[10:11], 0, s[46:47]
	global_load_dwordx4 v[224:227], v[34:35], off
	s_mov_b32 s46, 0x60000
	v_lshl_add_u64 v[34:35], v[6:7], 0, s[46:47]
	global_load_dwordx4 v[228:231], v[34:35], off
	ds_read_b128 v[236:239], v0 offset:0
	ds_read_b128 v[240:243], v0 offset:4224
	ds_read_b128 v[244:247], v0 offset:8448
	s_mov_b32 s46, 0x0
	v_lshl_add_u64 v[34:35], v[16:17], 0, s[46:47]
	ds_read_b128 v[248:251], v0 offset:12672
	s_waitcnt vmcnt(15) lgkmcnt(3)
	v_pk_fma_f32 v[238:239], v[238:239], v[234:235], v[114:115]
	v_pk_fma_f32 v[236:237], v[236:237], v[232:233], v[112:113]
	global_store_dwordx4 v[34:35], v[236:239], off
	s_mov_b32 s46, 0x0
	v_lshl_add_u64 v[34:35], v[12:13], 0, s[46:47]
	ds_read_b128 v[236:239], v0 offset:16896
	s_waitcnt vmcnt(15) lgkmcnt(3)
;     ...
;   for (int it = 0; it < 16; ++it) {
;     const int idx = it * 256 + tid; const int row = idx >> 5, c4 = (idx & 31) * 4;
;     f32x4 v = *(const f32x4*)(ct + row * 132 + c4);
;     epi(row, c4, v);
;   }
;   __syncthreads();
; DI void phase_outproj(KP p, int l, char* lds) {
;     ...
;   for (int j = lb; j < nsm; j += nlb) {
;     {
;       const int item = 2 * j + hb; const int bb = 2 * xcd + (item >> 4), m128 = (item >> 3) & 1, nt = item & 7;
;       const int m0 = (bb * 18 + 16 + m128) * 128, n0 = nt * 128;
;       const float* src = p->ctx + ((size_t)bb * CL + m128 * 128) * 1024;
;       float* dst = ctx1 + ((size_t)bb * CL + m128 * 128) * 1024;
;       const float* gt = mod + (size_t)16 * 3072 + 2048;
;       gemm_tile(Y + (size_t)m0 * 1024, 1024, wo + (size_t)n0 * 1024, 1024, 1024, lds, [&](int m, int n, f32x4 v) {
;         const size_t o = (size_t)m * 1024 + n0 + n;
;         f32x4 xv = *(const f32x4*)(src + o), g = *(const f32x4*)(gt + n0 + n);
;         f32x4 r = {xv[0] + g[0] * v[0], xv[1] + g[1] * v[1], xv[2] + g[2] * v[2], xv[3] + g[3] * v[3]};
;         *(f32x4*)(dst + o) = r; });
	v_pk_fma_f32 v[242:243], v[242:243], v[234:235], v[118:119]
	v_pk_fma_f32 v[240:241], v[240:241], v[232:233], v[116:117]
	global_store_dwordx4 v[34:35], v[240:243], off
	s_mov_b32 s46, 0x0
	v_lshl_add_u64 v[34:35], v[8:9], 0, s[46:47]
	ds_read_b128 v[240:243], v0 offset:21120
	s_waitcnt vmcnt(15) lgkmcnt(3)
	v_pk_fma_f32 v[246:247], v[246:247], v[234:235], v[122:123]
	v_pk_fma_f32 v[244:245], v[244:245], v[232:233], v[120:121]
	global_store_dwordx4 v[34:35], v[244:247], off
	s_mov_b32 s46, 0x0
	v_lshl_add_u64 v[34:35], v[4:5], 0, s[46:47]
	ds_read_b128 v[244:247], v0 offset:25344
	s_waitcnt vmcnt(15) lgkmcnt(3)
	v_pk_fma_f32 v[250:251], v[250:251], v[234:235], v[126:127]
	v_pk_fma_f32 v[248:249], v[248:249], v[232:233], v[124:125]
	global_store_dwordx4 v[34:35], v[248:251], off
	s_mov_b32 s46, 0x20000
	v_lshl_add_u64 v[34:35], v[16:17], 0, s[46:47]
	ds_read_b128 v[248:251], v0 offset:29568
	s_waitcnt vmcnt(15) lgkmcnt(3)
	v_pk_fma_f32 v[238:239], v[238:239], v[234:235], v[130:131]
	v_pk_fma_f32 v[236:237], v[236:237], v[232:233], v[128:129]
	global_store_dwordx4 v[34:35], v[236:239], off
	s_mov_b32 s46, 0x20000
	v_lshl_add_u64 v[34:35], v[12:13], 0, s[46:47]
	ds_read_b128 v[236:239], v0 offset:33792
	s_waitcnt vmcnt(15) lgkmcnt(3)
	v_pk_fma_f32 v[242:243], v[242:243], v[234:235], v[134:135]
	v_pk_fma_f32 v[240:241], v[240:241], v[232:233], v[132:133]
	global_store_dwordx4 v[34:35], v[240:243], off
	s_mov_b32 s46, 0x20000
	v_lshl_add_u64 v[34:35], v[8:9], 0, s[46:47]
	ds_read_b128 v[240:243], v0 offset:38016
	s_waitcnt vmcnt(15) lgkmcnt(3)
	v_pk_fma_f32 v[246:247], v[246:247], v[234:235], v[138:139]
	v_pk_fma_f32 v[244:245], v[244:245], v[232:233], v[136:137]
	global_store_dwordx4 v[34:35], v[244:247], off
	s_mov_b32 s46, 0x20000
	v_lshl_add_u64 v[34:35], v[4:5], 0, s[46:47]
	ds_read_b128 v[244:247], v0 offset:42240
	s_waitcnt vmcnt(15) lgkmcnt(3)
	v_pk_fma_f32 v[250:251], v[250:251], v[234:235], v[142:143]
	v_pk_fma_f32 v[248:249], v[248:249], v[232:233], v[140:141]
	global_store_dwordx4 v[34:35], v[248:251], off
	s_mov_b32 s46, 0x40000
	v_lshl_add_u64 v[34:35], v[16:17], 0, s[46:47]
	ds_read_b128 v[248:251], v0 offset:46464
	s_waitcnt vmcnt(15) lgkmcnt(3)
	v_pk_fma_f32 v[238:239], v[238:239], v[234:235], v[146:147]
	v_pk_fma_f32 v[236:237], v[236:237], v[232:233], v[144:145]
	global_store_dwordx4 v[34:35], v[236:239], off
	s_mov_b32 s46, 0x40000
	v_lshl_add_u64 v[34:35], v[12:13], 0, s[46:47]
	ds_read_b128 v[236:239], v0 offset:50688
	s_waitcnt vmcnt(15) lgkmcnt(3)
	v_pk_fma_f32 v[242:243], v[242:243], v[234:235], v[150:151]
	v_pk_fma_f32 v[240:241], v[240:241], v[232:233], v[148:149]
	global_store_dwordx4 v[34:35], v[240:243], off
	s_mov_b32 s46, 0x40000
	v_lshl_add_u64 v[34:35], v[8:9], 0, s[46:47]
	ds_read_b128 v[240:243], v0 offset:54912
	s_waitcnt vmcnt(15) lgkmcnt(3)
	v_pk_fma_f32 v[246:247], v[246:247], v[234:235], v[154:155]
	v_pk_fma_f32 v[244:245], v[244:245], v[232:233], v[152:153]
	global_store_dwordx4 v[34:35], v[244:247], off
	s_mov_b32 s46, 0x40000
	v_lshl_add_u64 v[34:35], v[4:5], 0, s[46:47]
	ds_read_b128 v[244:247], v0 offset:59136
	s_waitcnt vmcnt(15) lgkmcnt(3)
	v_pk_fma_f32 v[250:251], v[250:251], v[234:235], v[158:159]
	v_pk_fma_f32 v[248:249], v[248:249], v[232:233], v[156:157]
	global_store_dwordx4 v[34:35], v[248:251], off
	s_mov_b32 s46, 0x60000
	v_lshl_add_u64 v[34:35], v[16:17], 0, s[46:47]
	ds_read_b128 v[248:251], v0 offset:63360
	s_waitcnt vmcnt(15) lgkmcnt(3)
	v_pk_fma_f32 v[238:239], v[238:239], v[234:235], v[218:219]
	v_pk_fma_f32 v[236:237], v[236:237], v[232:233], v[216:217]
	global_store_dwordx4 v[34:35], v[236:239], off
	s_mov_b32 s46, 0x60000
	v_lshl_add_u64 v[34:35], v[12:13], 0, s[46:47]
	s_waitcnt vmcnt(15) lgkmcnt(2)
	v_pk_fma_f32 v[242:243], v[242:243], v[234:235], v[222:223]
	v_pk_fma_f32 v[240:241], v[240:241], v[232:233], v[220:221]
	global_store_dwordx4 v[34:35], v[240:243], off
	s_mov_b32 s46, 0x60000
	v_lshl_add_u64 v[34:35], v[8:9], 0, s[46:47]
	s_waitcnt vmcnt(15) lgkmcnt(1)
	v_pk_fma_f32 v[246:247], v[246:247], v[234:235], v[226:227]
	v_pk_fma_f32 v[244:245], v[244:245], v[232:233], v[224:225]
	global_store_dwordx4 v[34:35], v[244:247], off
	s_mov_b32 s46, 0x60000
	v_lshl_add_u64 v[34:35], v[4:5], 0, s[46:47]
	s_waitcnt vmcnt(15) lgkmcnt(0)
	v_pk_fma_f32 v[250:251], v[250:251], v[234:235], v[230:231]
	v_pk_fma_f32 v[248:249], v[248:249], v[232:233], v[228:229]
	global_store_dwordx4 v[34:35], v[248:251], off
	v_add_u32_e32 v0, 0x10800, v0
	s_mov_b64 s[42:43], 0x80000
	v_readlane_b32 s42, v254, 45
	s_add_i32 s48, s48, s42
	v_readlane_b32 s42, v253, 4
	s_add_i32 s50, s50, s69
	s_add_i32 s49, s49, s42
	s_cmp_gt_u32 s50, 15
	s_waitcnt lgkmcnt(0)
	s_barrier
	s_cbranch_scc0 .LBB0_356
